# v50: v46 with each in-proj load section's LDS-DMA pair issued before its LDS reads
# baseline (speedup 1.0000x reference)
; #define G_STAGE(bufoff, gbase, voff) do { _Pragma("unroll") for (int _i = 0; _i < 2; ++_i) \
;     __builtin_amdgcn_global_load_lds((const unsigned*)((const char*)(gbase) + (voff)[_i]), (LAS unsigned*)(lds + (bufoff) + ldsw + _i * 8192), 16, 0, 0); } while (0)
; #define G_LDA(dst, b, h) do { _Pragma("unroll") for (int m = 0; m < 4; ++m) _Pragma("unroll") for (int k = 0; k < 2; ++k) dst[m][k] = *(const LAS bf16x8*)(lds + G_SA(b, h) + aoff + m * 2048 + k * 1024); } while (0)
; #define G_LDB(dst, b, h) do { _Pragma("unroll") for (int n = 0; n < 2; ++n) _Pragma("unroll") for (int k = 0; k < 2; ++k) dst[n][k] = *(const LAS bf16x8*)(lds + G_SB(b, h) + boff + n * 2048 + k * 1024); } while (0)
; #define G_MMA(ai, bj, At, Bt) do { __builtin_amdgcn_s_setprio(1); _Pragma("unroll") for (int m = 0; m < 4; ++m) _Pragma("unroll") for (int n = 0; n < 2; ++n) _Pragma("unroll") for (int k = 0; k < 2; ++k) \
;     acc[ai][bj][m][n] = __builtin_amdgcn_mfma_f32_16x16x32_bf16(Bt[n][k], At[m][k], acc[ai][bj][m][n], 0, 0, 0); __builtin_amdgcn_s_setprio(0); } while (0)
; #define G_WAIT_V(n) asm volatile("s_waitcnt vmcnt(" #n ")" ::: "memory")
; #define G_WAIT_L(n) asm volatile("s_waitcnt lgkmcnt(" #n ")" ::: "memory")
; #define G_BAR __builtin_amdgcn_s_barrier()
; #define G_SCHED __builtin_amdgcn_sched_barrier(0)
; template <int GP> DI void gemm_phase(const Params& p, int l, int which, char* smem, int wv) {
;     ...
;       G_LDB(B0, 0, 0); G_SCHED; G_LDA(At, 0, 0); G_STAGE(G_SA(1, 1), a1 + hstep, voffA);
;       G_WAIT_L(8); G_BAR; G_WAIT_L(0); G_MMA(0, 0, At, B0); G_BAR; G_SCHED;
;       G_LDB(B1, 0, 1); G_STAGE(G_SB(0, 0), b2, vb0);
;       G_BAR; G_WAIT_L(0); G_MMA(0, 1, At, B1); G_BAR;
;       G_LDA(At, 0, 1); G_STAGE(G_SA(0, 0), a2, voffA);
;       G_BAR; G_WAIT_L(0); G_MMA(1, 0, At, B0); G_BAR; G_SCHED;
;       G_STAGE(G_SB(0, 1), b2, vb1);
;       G_WAIT_V(6); G_BAR; G_MMA(1, 1, At, B1); G_BAR;
.Lkf_top:
	global_load_lds_dwordx4 v138, s[100:101]
	s_add_i32 m0, s23, 0xe000
	s_nop 0
	global_load_lds_dwordx4 v140, s[100:101]
	ds_read_b128 v[148:151], v228
	ds_read_b128 v[152:155], v228 offset:1024
	ds_read_b128 v[156:159], v228 offset:2048
	ds_read_b128 v[160:163], v228 offset:3072
	ds_read_b128 v[164:167], v211
	ds_read_b128 v[168:171], v211 offset:1024
	ds_read_b128 v[172:175], v211 offset:2048
	ds_read_b128 v[176:179], v211 offset:3072
	ds_read_b128 v[180:183], v211 offset:4096
	ds_read_b128 v[184:187], v211 offset:5120
	ds_read_b128 v[188:191], v211 offset:6144
	ds_read_b128 v[192:195], v211 offset:7168
	s_waitcnt lgkmcnt(8)
	s_barrier
	s_waitcnt lgkmcnt(0)
	v_mfma_f32_16x16x32_bf16 v[62:65], v[148:151], v[164:167], v[62:65]
	v_mfma_f32_16x16x32_bf16 v[58:61], v[156:159], v[164:167], v[58:61]
	s_mov_b32 m0, s25
	v_mfma_f32_16x16x32_bf16 v[54:57], v[148:151], v[172:175], v[54:57]
	v_mfma_f32_16x16x32_bf16 v[50:53], v[156:159], v[172:175], v[50:53]
	v_mfma_f32_16x16x32_bf16 v[46:49], v[148:151], v[180:183], v[46:49]
	v_mfma_f32_16x16x32_bf16 v[42:45], v[156:159], v[180:183], v[42:45]
	v_mfma_f32_16x16x32_bf16 v[38:41], v[148:151], v[188:191], v[38:41]
	v_mfma_f32_16x16x32_bf16 v[34:37], v[156:159], v[188:191], v[34:37]
	v_mfma_f32_16x16x32_bf16 v[62:65], v[152:155], v[168:171], v[62:65]
	v_mfma_f32_16x16x32_bf16 v[58:61], v[160:163], v[168:171], v[58:61]
	v_mfma_f32_16x16x32_bf16 v[54:57], v[152:155], v[176:179], v[54:57]
	v_mfma_f32_16x16x32_bf16 v[50:53], v[160:163], v[176:179], v[50:53]
	v_mfma_f32_16x16x32_bf16 v[46:49], v[152:155], v[184:187], v[46:49]
	v_mfma_f32_16x16x32_bf16 v[42:45], v[160:163], v[184:187], v[42:45]
	v_mfma_f32_16x16x32_bf16 v[38:41], v[152:155], v[192:195], v[38:41]
	v_mfma_f32_16x16x32_bf16 v[34:37], v[160:163], v[192:195], v[34:37]
	s_barrier
	global_load_lds_dwordx4 v0, s[6:7]
	s_mov_b32 m0, s58
	s_nop 0
	global_load_lds_dwordx4 v136, s[6:7]
	ds_read_b128 v[196:199], v228 offset:16384
	ds_read_b128 v[200:203], v228 offset:17408
	ds_read_b128 v[204:207], v228 offset:18432
	ds_read_b128 v[238:241], v228 offset:19456
	s_barrier
	s_waitcnt lgkmcnt(0)
	v_mfma_f32_16x16x32_bf16 v[30:33], v[196:199], v[164:167], v[30:33]
	v_mfma_f32_16x16x32_bf16 v[26:29], v[204:207], v[164:167], v[26:29]
	s_mov_b32 m0, s23
	v_mfma_f32_16x16x32_bf16 v[22:25], v[196:199], v[172:175], v[22:25]
	v_mfma_f32_16x16x32_bf16 v[18:21], v[204:207], v[172:175], v[18:21]
	v_mfma_f32_16x16x32_bf16 v[14:17], v[196:199], v[180:183], v[14:17]
	v_mfma_f32_16x16x32_bf16 v[10:13], v[204:207], v[180:183], v[10:13]
	v_mfma_f32_16x16x32_bf16 v[6:9], v[196:199], v[188:191], v[6:9]
	v_mfma_f32_16x16x32_bf16 v[2:5], v[204:207], v[188:191], v[2:5]
	v_mfma_f32_16x16x32_bf16 v[30:33], v[200:203], v[168:171], v[30:33]
	v_mfma_f32_16x16x32_bf16 v[26:29], v[238:241], v[168:171], v[26:29]
	v_mfma_f32_16x16x32_bf16 v[22:25], v[200:203], v[176:179], v[22:25]
	v_mfma_f32_16x16x32_bf16 v[18:21], v[238:241], v[176:179], v[18:21]
	v_mfma_f32_16x16x32_bf16 v[14:17], v[200:203], v[184:187], v[14:17]
	v_mfma_f32_16x16x32_bf16 v[10:13], v[238:241], v[184:187], v[10:13]
	v_mfma_f32_16x16x32_bf16 v[6:9], v[200:203], v[192:195], v[6:9]
	v_mfma_f32_16x16x32_bf16 v[2:5], v[238:241], v[192:195], v[2:5]
	s_barrier
	global_load_lds_dwordx4 v132, s[8:9]
	s_mov_b32 m0, s59
	s_nop 0
	global_load_lds_dwordx4 v134, s[8:9]
	ds_read_b128 v[164:167], v211 offset:16384
	ds_read_b128 v[168:171], v211 offset:17408
	ds_read_b128 v[172:175], v211 offset:18432
	ds_read_b128 v[176:179], v211 offset:19456
	ds_read_b128 v[180:183], v211 offset:20480
	ds_read_b128 v[184:187], v211 offset:21504
	ds_read_b128 v[188:191], v211 offset:22528
	ds_read_b128 v[192:195], v211 offset:23552
	s_barrier
	s_waitcnt lgkmcnt(0)
	v_mfma_f32_16x16x32_bf16 v[66:69], v[148:151], v[164:167], v[66:69]
	v_mfma_f32_16x16x32_bf16 v[70:73], v[156:159], v[164:167], v[70:73]
	s_mov_b32 m0, s60
	v_mfma_f32_16x16x32_bf16 v[74:77], v[148:151], v[172:175], v[74:77]
	v_mfma_f32_16x16x32_bf16 v[78:81], v[156:159], v[172:175], v[78:81]
	v_mfma_f32_16x16x32_bf16 v[82:85], v[148:151], v[180:183], v[82:85]
	v_mfma_f32_16x16x32_bf16 v[86:89], v[156:159], v[180:183], v[86:89]
	v_mfma_f32_16x16x32_bf16 v[90:93], v[148:151], v[188:191], v[90:93]
	v_mfma_f32_16x16x32_bf16 v[94:97], v[156:159], v[188:191], v[94:97]
	v_mfma_f32_16x16x32_bf16 v[66:69], v[152:155], v[168:171], v[66:69]
	v_mfma_f32_16x16x32_bf16 v[70:73], v[160:163], v[168:171], v[70:73]
	v_mfma_f32_16x16x32_bf16 v[74:77], v[152:155], v[176:179], v[74:77]
	v_mfma_f32_16x16x32_bf16 v[78:81], v[160:163], v[176:179], v[78:81]
	v_mfma_f32_16x16x32_bf16 v[82:85], v[152:155], v[184:187], v[82:85]
	v_mfma_f32_16x16x32_bf16 v[86:89], v[160:163], v[184:187], v[86:89]
	v_mfma_f32_16x16x32_bf16 v[90:93], v[152:155], v[192:195], v[90:93]
	v_mfma_f32_16x16x32_bf16 v[94:97], v[160:163], v[192:195], v[94:97]
	s_barrier
	global_load_lds_dwordx4 v130, s[6:7]
	s_mov_b32 m0, s61
	s_nop 0
	global_load_lds_dwordx4 v142, s[6:7]
	s_waitcnt vmcnt(6)
	s_barrier
	v_mfma_f32_16x16x32_bf16 v[98:101], v[196:199], v[164:167], v[98:101]
	v_mfma_f32_16x16x32_bf16 v[102:105], v[204:207], v[164:167], v[102:105]
	s_add_u32 s100, s8, 0x80000
	s_addc_u32 s101, s9, 0
	s_mov_b32 m0, s62
	v_mfma_f32_16x16x32_bf16 v[106:109], v[196:199], v[172:175], v[106:109]
	v_mfma_f32_16x16x32_bf16 v[110:113], v[204:207], v[172:175], v[110:113]
	v_mfma_f32_16x16x32_bf16 v[114:117], v[196:199], v[180:183], v[114:117]
	v_mfma_f32_16x16x32_bf16 v[118:121], v[204:207], v[180:183], v[118:121]
	v_mfma_f32_16x16x32_bf16 v[122:125], v[196:199], v[188:191], v[122:125]
	v_mfma_f32_16x16x32_bf16 v[126:129], v[204:207], v[188:191], v[126:129]
	v_mfma_f32_16x16x32_bf16 v[98:101], v[200:203], v[168:171], v[98:101]
	v_mfma_f32_16x16x32_bf16 v[102:105], v[238:241], v[168:171], v[102:105]
	v_mfma_f32_16x16x32_bf16 v[106:109], v[200:203], v[176:179], v[106:109]
	v_mfma_f32_16x16x32_bf16 v[110:113], v[238:241], v[176:179], v[110:113]
	v_mfma_f32_16x16x32_bf16 v[114:117], v[200:203], v[184:187], v[114:117]
	v_mfma_f32_16x16x32_bf16 v[118:121], v[238:241], v[184:187], v[118:121]
	v_mfma_f32_16x16x32_bf16 v[122:125], v[200:203], v[192:195], v[122:125]
	v_mfma_f32_16x16x32_bf16 v[126:129], v[238:241], v[192:195], v[126:129]
	s_barrier
; #define G_STAGE(bufoff, gbase, voff) do { _Pragma("unroll") for (int _i = 0; _i < 2; ++_i) \
;     __builtin_amdgcn_global_load_lds((const unsigned*)((const char*)(gbase) + (voff)[_i]), (LAS unsigned*)(lds + (bufoff) + ldsw + _i * 8192), 16, 0, 0); } while (0)
; #define G_LDA(dst, b, h) do { _Pragma("unroll") for (int m = 0; m < 4; ++m) _Pragma("unroll") for (int k = 0; k < 2; ++k) dst[m][k] = *(const LAS bf16x8*)(lds + G_SA(b, h) + aoff + m * 2048 + k * 1024); } while (0)
; #define G_LDB(dst, b, h) do { _Pragma("unroll") for (int n = 0; n < 2; ++n) _Pragma("unroll") for (int k = 0; k < 2; ++k) dst[n][k] = *(const LAS bf16x8*)(lds + G_SB(b, h) + boff + n * 2048 + k * 1024); } while (0)
; #define G_MMA(ai, bj, At, Bt) do { __builtin_amdgcn_s_setprio(1); _Pragma("unroll") for (int m = 0; m < 4; ++m) _Pragma("unroll") for (int n = 0; n < 2; ++n) _Pragma("unroll") for (int k = 0; k < 2; ++k) \
;     acc[ai][bj][m][n] = __builtin_amdgcn_mfma_f32_16x16x32_bf16(Bt[n][k], At[m][k], acc[ai][bj][m][n], 0, 0, 0); __builtin_amdgcn_s_setprio(0); } while (0)
; #define G_WAIT_V(n) asm volatile("s_waitcnt vmcnt(" #n ")" ::: "memory")
; #define G_WAIT_L(n) asm volatile("s_waitcnt lgkmcnt(" #n ")" ::: "memory")
; #define G_BAR __builtin_amdgcn_s_barrier()
; #define G_SCHED __builtin_amdgcn_sched_barrier(0)
; template <int GP> DI void gemm_phase(const Params& p, int l, int which, char* smem, int wv) {
;     ...
;       G_LDB(B0, 1, 0); G_SCHED; G_LDA(At, 1, 0); G_STAGE(G_SA(0, 1), a2 + hstep, voffA);
;       G_WAIT_L(8); G_BAR; G_WAIT_L(0); G_MMA(0, 0, At, B0); G_BAR; G_SCHED;
;       G_LDB(B1, 1, 1); G_STAGE(G_SB(1, 0), b3, vb0);
;       G_BAR; G_WAIT_L(0); G_MMA(0, 1, At, B1); G_BAR;
;       G_LDA(At, 1, 1); G_STAGE(G_SA(1, 0), a3, voffA);
;       G_BAR; G_WAIT_L(0); G_MMA(1, 0, At, B0); G_BAR; G_SCHED;
;       G_STAGE(G_SB(1, 1), b3, vb1);
;       G_WAIT_V(6); G_BAR; G_MMA(1, 1, At, B1); G_BAR;
	global_load_lds_dwordx4 v132, s[100:101]
	s_mov_b32 m0, s63
	s_nop 0
	global_load_lds_dwordx4 v134, s[100:101]
	ds_read_b128 v[148:151], v228 offset:32768
	ds_read_b128 v[152:155], v228 offset:33792
	ds_read_b128 v[156:159], v228 offset:34816
	ds_read_b128 v[160:163], v228 offset:35840
	ds_read_b128 v[164:167], v211 offset:32768
	ds_read_b128 v[168:171], v211 offset:33792
	ds_read_b128 v[172:175], v211 offset:34816
	ds_read_b128 v[176:179], v211 offset:35840
	ds_read_b128 v[180:183], v211 offset:36864
	ds_read_b128 v[184:187], v211 offset:37888
	ds_read_b128 v[188:191], v211 offset:38912
	ds_read_b128 v[192:195], v211 offset:39936
	s_waitcnt lgkmcnt(8)
	s_barrier
	s_waitcnt lgkmcnt(0)
	v_mfma_f32_16x16x32_bf16 v[62:65], v[148:151], v[164:167], v[62:65]
	v_mfma_f32_16x16x32_bf16 v[58:61], v[156:159], v[164:167], v[58:61]
	s_mov_b32 m0, s21
	s_add_u32 s100, s6, s16
	s_addc_u32 s101, s7, s17
	v_mfma_f32_16x16x32_bf16 v[54:57], v[148:151], v[172:175], v[54:57]
	v_mfma_f32_16x16x32_bf16 v[50:53], v[156:159], v[172:175], v[50:53]
	v_mfma_f32_16x16x32_bf16 v[46:49], v[148:151], v[180:183], v[46:49]
	v_mfma_f32_16x16x32_bf16 v[42:45], v[156:159], v[180:183], v[42:45]
	v_mfma_f32_16x16x32_bf16 v[38:41], v[148:151], v[188:191], v[38:41]
	v_mfma_f32_16x16x32_bf16 v[34:37], v[156:159], v[188:191], v[34:37]
	v_mfma_f32_16x16x32_bf16 v[62:65], v[152:155], v[168:171], v[62:65]
	v_mfma_f32_16x16x32_bf16 v[58:61], v[160:163], v[168:171], v[58:61]
	v_mfma_f32_16x16x32_bf16 v[54:57], v[152:155], v[176:179], v[54:57]
	v_mfma_f32_16x16x32_bf16 v[50:53], v[160:163], v[176:179], v[50:53]
	v_mfma_f32_16x16x32_bf16 v[46:49], v[152:155], v[184:187], v[46:49]
	v_mfma_f32_16x16x32_bf16 v[42:45], v[160:163], v[184:187], v[42:45]
	v_mfma_f32_16x16x32_bf16 v[38:41], v[152:155], v[192:195], v[38:41]
	v_mfma_f32_16x16x32_bf16 v[34:37], v[160:163], v[192:195], v[34:37]
	s_barrier
	global_load_lds_dwordx4 v0, s[100:101]
	s_mov_b32 m0, s64
	s_nop 0
	global_load_lds_dwordx4 v136, s[100:101]
	ds_read_b128 v[196:199], v228 offset:49152
	ds_read_b128 v[200:203], v228 offset:50176
	ds_read_b128 v[204:207], v228 offset:51200
	ds_read_b128 v[238:241], v228 offset:52224
	s_barrier
	s_waitcnt lgkmcnt(0)
	v_mfma_f32_16x16x32_bf16 v[30:33], v[196:199], v[164:167], v[30:33]
	v_mfma_f32_16x16x32_bf16 v[26:29], v[204:207], v[164:167], v[26:29]
	s_mov_b32 m0, s65
	s_add_u32 s100, s8, s16
	s_addc_u32 s101, s9, s17
	v_mfma_f32_16x16x32_bf16 v[22:25], v[196:199], v[172:175], v[22:25]
	v_mfma_f32_16x16x32_bf16 v[18:21], v[204:207], v[172:175], v[18:21]
	v_mfma_f32_16x16x32_bf16 v[14:17], v[196:199], v[180:183], v[14:17]
	v_mfma_f32_16x16x32_bf16 v[10:13], v[204:207], v[180:183], v[10:13]
	v_mfma_f32_16x16x32_bf16 v[6:9], v[196:199], v[188:191], v[6:9]
	v_mfma_f32_16x16x32_bf16 v[2:5], v[204:207], v[188:191], v[2:5]
	v_mfma_f32_16x16x32_bf16 v[30:33], v[200:203], v[168:171], v[30:33]
	v_mfma_f32_16x16x32_bf16 v[26:29], v[238:241], v[168:171], v[26:29]
	v_mfma_f32_16x16x32_bf16 v[22:25], v[200:203], v[176:179], v[22:25]
	v_mfma_f32_16x16x32_bf16 v[18:21], v[238:241], v[176:179], v[18:21]
	v_mfma_f32_16x16x32_bf16 v[14:17], v[200:203], v[184:187], v[14:17]
	v_mfma_f32_16x16x32_bf16 v[10:13], v[238:241], v[184:187], v[10:13]
	v_mfma_f32_16x16x32_bf16 v[6:9], v[200:203], v[192:195], v[6:9]
	v_mfma_f32_16x16x32_bf16 v[2:5], v[238:241], v[192:195], v[2:5]
	s_barrier
	global_load_lds_dwordx4 v132, s[100:101]
	s_mov_b32 m0, s66
	s_nop 0
	global_load_lds_dwordx4 v134, s[100:101]
	ds_read_b128 v[164:167], v211 offset:49152
	ds_read_b128 v[168:171], v211 offset:50176
	ds_read_b128 v[172:175], v211 offset:51200
	ds_read_b128 v[176:179], v211 offset:52224
	ds_read_b128 v[180:183], v211 offset:53248
	ds_read_b128 v[184:187], v211 offset:54272
	ds_read_b128 v[188:191], v211 offset:55296
	ds_read_b128 v[192:195], v211 offset:56320
	s_barrier
	s_waitcnt lgkmcnt(0)
	v_mfma_f32_16x16x32_bf16 v[66:69], v[148:151], v[164:167], v[66:69]
	v_mfma_f32_16x16x32_bf16 v[70:73], v[156:159], v[164:167], v[70:73]
	s_mov_b32 m0, s67
	s_add_u32 s100, s6, s16
	s_addc_u32 s101, s7, s17
	v_mfma_f32_16x16x32_bf16 v[74:77], v[148:151], v[172:175], v[74:77]
	v_mfma_f32_16x16x32_bf16 v[78:81], v[156:159], v[172:175], v[78:81]
	v_mfma_f32_16x16x32_bf16 v[82:85], v[148:151], v[180:183], v[82:85]
	v_mfma_f32_16x16x32_bf16 v[86:89], v[156:159], v[180:183], v[86:89]
	v_mfma_f32_16x16x32_bf16 v[90:93], v[148:151], v[188:191], v[90:93]
	v_mfma_f32_16x16x32_bf16 v[94:97], v[156:159], v[188:191], v[94:97]
	v_mfma_f32_16x16x32_bf16 v[66:69], v[152:155], v[168:171], v[66:69]
	v_mfma_f32_16x16x32_bf16 v[70:73], v[160:163], v[168:171], v[70:73]
	v_mfma_f32_16x16x32_bf16 v[74:77], v[152:155], v[176:179], v[74:77]
	v_mfma_f32_16x16x32_bf16 v[78:81], v[160:163], v[176:179], v[78:81]
	v_mfma_f32_16x16x32_bf16 v[82:85], v[152:155], v[184:187], v[82:85]
	v_mfma_f32_16x16x32_bf16 v[86:89], v[160:163], v[184:187], v[86:89]
	v_mfma_f32_16x16x32_bf16 v[90:93], v[152:155], v[192:195], v[90:93]
	v_mfma_f32_16x16x32_bf16 v[94:97], v[160:163], v[192:195], v[94:97]
	s_barrier
	global_load_lds_dwordx4 v130, s[100:101]
	s_mov_b32 m0, s68
	s_nop 0
	global_load_lds_dwordx4 v142, s[100:101]
	s_waitcnt vmcnt(6)
	s_barrier
	v_mfma_f32_16x16x32_bf16 v[98:101], v[196:199], v[164:167], v[98:101]
	v_mfma_f32_16x16x32_bf16 v[102:105], v[204:207], v[164:167], v[102:105]
	s_add_i32 m0, s23, 0xc000
	v_mfma_f32_16x16x32_bf16 v[106:109], v[196:199], v[172:175], v[106:109]
	v_mfma_f32_16x16x32_bf16 v[110:113], v[204:207], v[172:175], v[110:113]
	v_mfma_f32_16x16x32_bf16 v[114:117], v[196:199], v[180:183], v[114:117]
	v_mfma_f32_16x16x32_bf16 v[118:121], v[204:207], v[180:183], v[118:121]
	v_mfma_f32_16x16x32_bf16 v[122:125], v[196:199], v[188:191], v[122:125]
	v_mfma_f32_16x16x32_bf16 v[126:129], v[204:207], v[188:191], v[126:129]
	v_mfma_f32_16x16x32_bf16 v[98:101], v[200:203], v[168:171], v[98:101]
	s_add_i32 s50, s50, 2
	s_add_u32 s2, s2, 0x100
	s_addc_u32 s3, s3, 0
	v_mfma_f32_16x16x32_bf16 v[102:105], v[238:241], v[168:171], v[102:105]
	s_add_u32 s8, s28, s2
	s_addc_u32 s9, s29, s3
	v_mfma_f32_16x16x32_bf16 v[106:109], v[200:203], v[176:179], v[106:109]
	s_add_u32 s100, s8, 0x80080
	s_addc_u32 s101, s9, 0
	v_mfma_f32_16x16x32_bf16 v[110:113], v[238:241], v[176:179], v[110:113]
	s_add_u32 s8, s8, 0x100
	s_addc_u32 s9, s9, 0
	v_mfma_f32_16x16x32_bf16 v[114:117], v[200:203], v[184:187], v[114:117]
	s_add_u32 s6, s74, s2
	s_addc_u32 s7, s75, s3
	v_mfma_f32_16x16x32_bf16 v[118:121], v[238:241], v[184:187], v[118:121]
	v_mfma_f32_16x16x32_bf16 v[122:125], v[200:203], v[192:195], v[122:125]
	v_mfma_f32_16x16x32_bf16 v[126:129], v[238:241], v[192:195], v[126:129]
	s_cmp_gt_u32 s50, 29
	s_barrier
	s_cbranch_scc1 .LBB0_219
	s_cmpk_lg_i32 s2, 0xf00
	s_cbranch_scc1 .Lkf_top
